# P12 row pass: loop-invariant gain vector loaded once before the row loop (was reloaded per row chunk behind vmcnt(0) waits)
# baseline (speedup 1.0000x reference)
; __device__ __forceinline__ float bflo(unsigned w) { return __uint_as_float(w << 16); }
; __device__ __forceinline__ float bfhi(unsigned w) { return __uint_as_float(w & 0xffff0000u); }
; template <class Tv> __device__ __forceinline__ Tv ntload(const Tv* p) { return __builtin_nontemporal_load(p); }
; __device__ __forceinline__ float wave_sum(float v) {
; #pragma unroll
;     for (int o = 1; o < 64; o <<= 1) v += __shfl_xor(v, o);
;     return v;
; }
; template <bool BASE_BF, bool OUT_BF>
; __device__ __forceinline__ void row_pass(const bf16* Y, const void* basev, int ldb, const float* gA, void* outv, int ldo, float* rs, const float* pin, int gw, int NGW, int lane) {
;     const float* base = (const float*)basev; const bf16* baseb = (const bf16*)basev; float* outh = (float*)outv; bf16* outb = (bf16*)outv;
;     for (int row0 = gw; row0 < T; row0 += 2 * NGW) {
;         f32x4 h[2][8]; v4u yw[2][4];
; #pragma unroll
;         for (int k = 0; k < 2; ++k)
; #pragma unroll
;             for (int j = 0; j < 4; ++j) { const size_t row = (size_t)(row0 + k * NGW); const int c = j * 512 + lane * 8; yw[k][j] = ntload((const v4u*)(Y + row * DM + c));
;                 if constexpr (BASE_BF) { const v4u bw = ntload((const v4u*)(baseb + row * ldb + c)); h[k][2 * j] = (f32x4){bflo(bw.x), bfhi(bw.x), bflo(bw.y), bfhi(bw.y)}; h[k][2 * j + 1] = (f32x4){bflo(bw.z), bfhi(bw.z), bflo(bw.w), bfhi(bw.w)}; }
;                 else { h[k][2 * j] = ntload((const f32x4*)(base + row * ldb + c)); h[k][2 * j + 1] = ntload((const f32x4*)(base + row * ldb + c + 4)); } }
; #pragma unroll
;         for (int k = 0; k < 2; ++k) { const size_t row = (size_t)(row0 + k * NGW);
;             f32x4 y[8]; float s = 0.f;
; #pragma unroll
;             for (int j = 0; j < 4; ++j) { const v4u w = yw[k][j]; y[2 * j] = (f32x4){bflo(w.x), bfhi(w.x), bflo(w.y), bfhi(w.y)}; y[2 * j + 1] = (f32x4){bflo(w.z), bfhi(w.z), bflo(w.w), bfhi(w.w)}; }
; #pragma unroll
;             for (int j = 0; j < 8; ++j) s += (y[j].x * y[j].x + y[j].y * y[j].y) + (y[j].z * y[j].z + y[j].w * y[j].w);
;             const float r1 = 1.0f / sqrtf(wave_sum(s) * (1.f / DM) + NORM_EPS); float s2 = 0.f;
; #pragma unroll
;             for (int j = 0; j < 4; ++j) { const int c = j * 512 + lane * 8; const f32x4 g0 = *(const f32x4*)(gA + c), g1 = *(const f32x4*)(gA + c + 4);
.LBB0_1597:
	s_cmp_lt_i32 s60, 13
	s_cselect_b64 s[4:5], -1, 0
	s_and_b64 s[6:7], s[4:5], s[0:1]
	s_andn2_b64 vcc, exec, s[6:7]
	s_cbranch_vccnz .LBB0_1605
	s_cmpk_gt_i32 s10, 0x7fff
	s_movk_i32 s3, 0x7fff
	s_cbranch_scc1 .LBB0_1605
	v_mbcnt_lo_u32_b32 v2, -1, 0
	v_mbcnt_hi_u32_b32 v2, -1, v2
	v_and_b32_e32 v3, 64, v2
	v_add_u32_e32 v3, 64, v3
	v_xor_b32_e32 v4, 1, v2
	v_cmp_lt_i32_e32 vcc, v4, v3
	s_add_u32 s14, s34, 0x8a00000
	s_addc_u32 s15, s35, 0
	v_cndmask_b32_e32 v4, v2, v4, vcc
	v_lshlrev_b32_e32 v88, 2, v4
	v_xor_b32_e32 v4, 2, v2
	v_cmp_lt_i32_e32 vcc, v4, v3
	s_lshl_b32 s8, s67, 4
	s_add_i32 s4, s10, s33
	v_cndmask_b32_e32 v4, v2, v4, vcc
	v_lshlrev_b32_e32 v89, 2, v4
	v_xor_b32_e32 v4, 4, v2
	v_cmp_lt_i32_e32 vcc, v4, v3
	v_lshlrev_b32_e32 v58, 5, v198
	v_mov_b32_e32 v59, 0
	v_cndmask_b32_e32 v4, v2, v4, vcc
	v_lshlrev_b32_e32 v90, 2, v4
	v_xor_b32_e32 v4, 8, v2
	v_cmp_lt_i32_e32 vcc, v4, v3
	s_ashr_i32 s5, s4, 31
	s_ashr_i32 s9, s8, 31
	v_cndmask_b32_e32 v4, v2, v4, vcc
	v_lshlrev_b32_e32 v91, 2, v4
	v_xor_b32_e32 v4, 16, v2
	v_cmp_lt_i32_e32 vcc, v4, v3
	s_ashr_i32 s11, s10, 31
	s_lshl_b64 s[16:17], s[4:5], 2
	v_cndmask_b32_e32 v4, v2, v4, vcc
	v_lshlrev_b32_e32 v92, 2, v4
	v_xor_b32_e32 v4, 32, v2
	v_cmp_lt_i32_e32 vcc, v4, v3
	v_mov_b32_e32 v3, v59
	s_lshl_b64 s[18:19], s[8:9], 2
	v_cndmask_b32_e32 v2, v2, v4, vcc
	v_lshlrev_b32_e32 v93, 2, v2
	v_or_b32_e32 v2, 0x1000, v58
	s_lshl_b64 s[12:13], s[10:11], 12
	v_lshl_add_u64 v[62:63], s[44:45], 0, v[2:3]
	v_or_b32_e32 v2, 0x1800, v58
	s_add_u32 s20, s34, s12
	v_lshl_add_u64 v[60:61], s[44:45], 0, v[58:59]
	v_lshl_add_u64 v[64:65], s[44:45], 0, v[2:3]
	s_addc_u32 s21, s35, s13
	s_lshl_b64 s[22:23], s[8:9], 12
	s_lshl_b64 s[24:25], s[4:5], 13
	v_readlane_b32 s44, v250, 8
	v_readlane_b32 s45, v250, 9
	s_add_u32 s24, s44, s24
	s_addc_u32 s25, s45, s25
	s_lshl_b64 s[26:27], s[8:9], 13
	s_lshl_b64 s[4:5], s[4:5], 12
	s_add_u32 s36, s30, s4
	s_addc_u32 s37, s31, s5
	s_add_u32 s38, s34, s4
	s_addc_u32 s39, s35, s5
	s_lshl_b64 s[40:41], s[10:11], 2
	s_add_u32 s42, s30, s12
	s_addc_u32 s43, s31, s13
	s_lshl_b64 s[4:5], s[10:11], 13
	v_readlane_b32 s46, v250, 10
	v_readlane_b32 s47, v250, 11
	v_readlane_b32 s51, v250, 15
	v_readlane_b32 s52, v250, 16
	s_add_u32 s12, s44, s4
	v_cmp_eq_u32_e64 s[0:1], 0, v198
	s_movk_i32 s62, 0x1000
	v_lshlrev_b32_e32 v66, 4, v198
	v_mov_b32_e32 v67, v59
	s_addc_u32 s13, s45, s5
	s_mov_b32 s9, 0x31a00000
	s_mov_b64 s[44:45], 0x1000
	s_mov_b64 s[46:47], 0x1800
	s_mov_b32 s11, 0xffff0000
	v_mov_b32_e32 v94, 0x358637bd
	s_mov_b32 s51, 0xf800000
	v_mov_b32_e32 v95, 0x260
	s_mov_b32 s52, s10
	v_readlane_b32 s48, v250, 12
	v_readlane_b32 s49, v250, 13
	v_readlane_b32 s50, v250, 14
	v_readlane_b32 s53, v250, 17
	v_readlane_b32 s54, v250, 18
	v_readlane_b32 s55, v250, 19
	v_readlane_b32 s56, v250, 20
	v_readlane_b32 s57, v250, 21
	v_readlane_b32 s58, v250, 22
	v_readlane_b32 s59, v250, 23
	global_load_dwordx4 v[200:203], v[60:61], off offset:16
	global_load_dwordx4 v[204:207], v[60:61], off
	global_load_dwordx4 v[208:211], v[60:61], off offset:2048
	global_load_dwordx4 v[212:215], v[60:61], off offset:2064
	global_load_dwordx4 v[216:219], v[62:63], off
	global_load_dwordx4 v[220:223], v[62:63], off offset:16
	global_load_dwordx4 v[224:227], v[64:65], off
	global_load_dwordx4 v[228:231], v[64:65], off offset:16
	s_branch .LBB0_1601

; __device__ __forceinline__ float bflo(unsigned w) { return __uint_as_float(w << 16); }
; __device__ __forceinline__ float bfhi(unsigned w) { return __uint_as_float(w & 0xffff0000u); }
; template <class Tv> __device__ __forceinline__ Tv ntload(const Tv* p) { return __builtin_nontemporal_load(p); }
; template <bool BASE_BF, bool OUT_BF>
; __device__ __forceinline__ void row_pass(const bf16* Y, const void* basev, int ldb, const float* gA, void* outv, int ldo, float* rs, const float* pin, int gw, int NGW, int lane) {
;     ...
;     for (int row0 = gw; row0 < T; row0 += 2 * NGW) {
;         f32x4 h[2][8]; v4u yw[2][4];
; #pragma unroll
;         for (int k = 0; k < 2; ++k)
; #pragma unroll
;             for (int j = 0; j < 4; ++j) { const size_t row = (size_t)(row0 + k * NGW); const int c = j * 512 + lane * 8; yw[k][j] = ntload((const v4u*)(Y + row * DM + c));
;                 if constexpr (BASE_BF) { const v4u bw = ntload((const v4u*)(baseb + row * ldb + c)); h[k][2 * j] = (f32x4){bflo(bw.x), bfhi(bw.x), bflo(bw.y), bfhi(bw.y)}; h[k][2 * j + 1] = (f32x4){bflo(bw.z), bfhi(bw.z), bflo(bw.w), bfhi(bw.w)}; }
;                 else { h[k][2 * j] = ntload((const f32x4*)(base + row * ldb + c)); h[k][2 * j + 1] = ntload((const f32x4*)(base + row * ldb + c + 4)); } }
; #pragma unroll
;         for (int k = 0; k < 2; ++k) { const size_t row = (size_t)(row0 + k * NGW);
;             f32x4 y[8]; float s = 0.f;
; #pragma unroll
;             for (int j = 0; j < 4; ++j) { const v4u w = yw[k][j]; y[2 * j] = (f32x4){bflo(w.x), bfhi(w.x), bflo(w.y), bfhi(w.y)}; y[2 * j + 1] = (f32x4){bflo(w.z), bfhi(w.z), bflo(w.w), bfhi(w.w)}; }
; #pragma unroll
;             for (int j = 0; j < 8; ++j) s += (y[j].x * y[j].x + y[j].y * y[j].y) + (y[j].z * y[j].z + y[j].w * y[j].w);
;             const float r1 = 1.0f / sqrtf(wave_sum(s) * (1.f / DM) + NORM_EPS); float s2 = 0.f;
.LBB0_1601:
	s_waitcnt lgkmcnt(0)
	v_lshl_add_u64 v[2:3], s[20:21], 0, v[66:67]
	v_add_co_u32_e32 v2, vcc, 0x31a00000, v2
	v_lshl_add_u64 v[4:5], s[12:13], 0, v[58:59]
	s_nop 0
	v_addc_co_u32_e32 v3, vcc, 0, v3, vcc
	global_load_dwordx4 v[6:9], v[2:3], off offset:1024 nt
	s_waitcnt lgkmcnt(0)
	global_load_dwordx4 v[10:13], v[2:3], off offset:2048 nt
	global_load_dwordx4 v[14:17], v[2:3], off offset:3072 nt
	global_load_dwordx4 v[18:21], v[2:3], off nt
	global_load_dwordx4 v[104:107], v[4:5], off offset:16 nt
	global_load_dwordx4 v[108:111], v[4:5], off nt
	global_load_dwordx4 v[112:115], v[4:5], off offset:2064 nt
	global_load_dwordx4 v[116:119], v[4:5], off offset:2048 nt
	v_lshl_add_u64 v[2:3], s[38:39], 0, v[66:67]
	s_waitcnt vmcnt(0)
	v_lshlrev_b32_e32 v128, 16, v8
	v_and_b32_e32 v129, 0xffff0000, v8
	v_lshlrev_b32_e32 v137, 16, v7
	v_and_b32_e32 v131, 0xffff0000, v20
	v_and_b32_e32 v130, 0xffff0000, v18
	v_and_b32_e32 v135, 0xffff0000, v21
	v_and_b32_e32 v134, 0xffff0000, v19
	v_lshlrev_b32_e32 v77, 16, v20
	v_lshlrev_b32_e32 v76, 16, v18
	v_lshlrev_b32_e32 v133, 16, v21
	v_lshlrev_b32_e32 v132, 16, v19
	v_lshlrev_b32_e32 v136, 16, v6
	v_and_b32_e32 v139, 0xffff0000, v7
	v_and_b32_e32 v138, 0xffff0000, v6
	v_lshlrev_b32_e32 v140, 16, v9
	v_and_b32_e32 v141, 0xffff0000, v9
	v_pk_mul_f32 v[6:7], v[130:131], v[130:131]
	v_pk_mul_f32 v[8:9], v[134:135], v[134:135]
	v_lshlrev_b32_e32 v83, 16, v10
	v_and_b32_e32 v81, 0xffff0000, v10
	v_lshlrev_b32_e32 v78, 16, v11
	v_and_b32_e32 v79, 0xffff0000, v11
	v_pk_mul_f32 v[10:11], v[138:139], v[138:139]
	v_pk_fma_f32 v[6:7], v[76:77], v[76:77], v[6:7]
	v_pk_fma_f32 v[8:9], v[132:133], v[132:133], v[8:9]
	v_lshlrev_b32_e32 v84, 16, v12
	v_and_b32_e32 v85, 0xffff0000, v12
	v_lshlrev_b32_e32 v86, 16, v13
	v_and_b32_e32 v87, 0xffff0000, v13
	v_lshlrev_b32_e32 v72, 16, v14
	v_and_b32_e32 v73, 0xffff0000, v14
	v_mul_f32_e32 v82, v128, v128
	v_mul_f32_e32 v12, v129, v129
	v_mov_b32_e32 v13, v83
	v_mul_f32_e32 v14, v141, v141
	v_pk_fma_f32 v[10:11], v[136:137], v[136:137], v[10:11]
	v_pk_add_f32 v[6:7], v[6:7], v[8:9]
	v_lshlrev_b32_e32 v74, 16, v15
	v_and_b32_e32 v75, 0xffff0000, v15
	v_mul_f32_e32 v25, v81, v81
	v_mul_f32_e32 v28, v78, v78
	v_mul_f32_e32 v29, v79, v79
	v_pk_add_f32 v[12:13], v[82:83], v[12:13]
	v_pk_mul_f32 v[26:27], v[82:83], v[82:83]
	v_pk_fma_f32 v[14:15], v[140:141], v[140:141], v[14:15] op_sel_hi:[1,1,0]
	v_pk_add_f32 v[8:9], v[10:11], v[10:11] op_sel:[0,1] op_sel_hi:[1,0]
	v_pk_add_f32 v[6:7], v[6:7], v[6:7] op_sel:[0,1] op_sel_hi:[1,0]
	v_mov_b32_e32 v13, v27
	v_mov_b32_e32 v15, v25
	v_mov_b32_e32 v9, v29
	v_mov_b32_e32 v7, v28
	v_lshlrev_b32_e32 v70, 16, v16
	v_and_b32_e32 v71, 0xffff0000, v16
	v_mul_f32_e32 v16, v84, v84
	v_mul_f32_e32 v18, v86, v86
	v_pk_add_f32 v[12:13], v[12:13], v[14:15]
	v_pk_add_f32 v[6:7], v[6:7], v[8:9]
	v_lshlrev_b32_e32 v68, 16, v17
	v_and_b32_e32 v69, 0xffff0000, v17
	v_mul_f32_e32 v20, v72, v72
	v_mul_f32_e32 v22, v74, v74
	v_pk_fma_f32 v[16:17], v[84:85], v[84:85], v[16:17] op_sel_hi:[1,1,0]
	v_pk_fma_f32 v[18:19], v[86:87], v[86:87], v[18:19] op_sel_hi:[1,1,0]
	v_pk_add_f32 v[6:7], v[12:13], v[6:7]
	v_pk_fma_f32 v[20:21], v[72:73], v[72:73], v[20:21] op_sel_hi:[1,1,0]
	v_pk_fma_f32 v[22:23], v[74:75], v[74:75], v[22:23] op_sel_hi:[1,1,0]
	v_pk_add_f32 v[10:11], v[16:17], v[18:19]
	v_pk_add_f32 v[6:7], v[6:7], v[6:7] op_sel_hi:[0,1]
	v_mul_f32_e32 v24, v70, v70
	v_mul_f32_e32 v20, v68, v68
	v_mul_f32_e32 v22, v69, v69
	v_mov_b32_e32 v25, v11
	v_mul_f32_e32 v6, v71, v71
	v_pk_add_f32 v[10:11], v[20:21], v[22:23]
	v_pk_add_f32 v[6:7], v[24:25], v[6:7]
	v_lshl_add_u64 v[8:9], v[4:5], 0, s[46:47]
	v_pk_add_f32 v[6:7], v[6:7], v[10:11]
	v_mov_b32_e32 v146, v132
	v_add_f32_e32 v10, v6, v7
	ds_bpermute_b32 v11, v88, v10
	v_lshl_add_u64 v[6:7], v[4:5], 0, s[44:45]
	v_add_co_u32_e32 v4, vcc, s62, v4
	v_mov_b32_e32 v147, v134
	s_waitcnt lgkmcnt(0)
	v_add_f32_e32 v10, v10, v11
	ds_bpermute_b32 v11, v89, v10
	v_addc_co_u32_e32 v5, vcc, 0, v5, vcc
	global_load_dwordx4 v[120:123], v[4:5], off nt
	global_load_dwordx4 v[124:127], v[6:7], off offset:16 nt
	global_load_dwordx4 v[54:57], v[4:5], off offset:2048 nt
	global_load_dwordx4 v[50:53], v[8:9], off offset:16 nt
	v_add_co_u32_e32 v2, vcc, s9, v2
	s_waitcnt lgkmcnt(0)
	v_add_f32_e32 v10, v10, v11
	ds_bpermute_b32 v11, v90, v10
	v_addc_co_u32_e32 v3, vcc, 0, v3, vcc
	v_lshl_add_u64 v[4:5], s[24:25], 0, v[58:59]
	global_load_dwordx4 v[26:29], v[4:5], off offset:16 nt
	global_load_dwordx4 v[30:33], v[4:5], off nt
	s_waitcnt lgkmcnt(0)
	v_add_f32_e32 v6, v10, v11
	ds_bpermute_b32 v7, v91, v6
	global_load_dwordx4 v[46:49], v[2:3], off nt
	global_load_dwordx4 v[42:45], v[2:3], off offset:1024 nt
	global_load_dwordx4 v[18:21], v[4:5], off offset:2064 nt
	global_load_dwordx4 v[22:25], v[4:5], off offset:2048 nt
	v_mov_b32_e32 v134, v133
	s_waitcnt lgkmcnt(0)
	v_add_f32_e32 v8, v6, v7
	ds_bpermute_b32 v9, v92, v8
	v_lshl_add_u64 v[6:7], v[4:5], 0, s[44:45]
	s_waitcnt lgkmcnt(0)
	v_add_f32_e32 v10, v8, v9
	ds_bpermute_b32 v11, v93, v10
	v_add_co_u32_e32 v8, vcc, s62, v4
	s_waitcnt lgkmcnt(0)
; __device__ __forceinline__ unsigned pk2(float lo, float hi) { return f2bf(lo) | (f2bf(hi) << 16); }
; template <class Tv> __device__ __forceinline__ void ntstore(Tv v, Tv* p) { __builtin_nontemporal_store(v, p); }
; template <bool BASE_BF, bool OUT_BF>
; __device__ __forceinline__ void row_pass(const bf16* Y, const void* basev, int ldb, const float* gA, void* outv, int ldo, float* rs, const float* pin, int gw, int NGW, int lane) {
;     ...
;             for (int j = 0; j < 8; ++j) s += (y[j].x * y[j].x + y[j].y * y[j].y) + (y[j].z * y[j].z + y[j].w * y[j].w);
;             const float r1 = 1.0f / sqrtf(wave_sum(s) * (1.f / DM) + NORM_EPS); float s2 = 0.f;
; #pragma unroll
;             for (int j = 0; j < 4; ++j) { const int c = j * 512 + lane * 8; const f32x4 g0 = *(const f32x4*)(gA + c), g1 = *(const f32x4*)(gA + c + 4);
;                 h[k][2 * j] = h[k][2 * j] + y[2 * j] * r1 * g0; h[k][2 * j + 1] = h[k][2 * j + 1] + y[2 * j + 1] * r1 * g1;
;                 if constexpr (OUT_BF) { const f32x4 a = h[k][2 * j], b = h[k][2 * j + 1]; v4u o; o.x = pk2(a.x, a.y); o.y = pk2(a.z, a.w); o.z = pk2(b.x, b.y); o.w = pk2(b.z, b.w); ntstore(o, (v4u*)(outb + row * ldo + c)); }
;                 else { ntstore(h[k][2 * j], (f32x4*)(outh + row * ldo + c)); ntstore(h[k][2 * j + 1], (f32x4*)(outh + row * ldo + c + 4)); } }
	v_add_f32_e32 v10, v10, v11
	v_addc_co_u32_e32 v9, vcc, 0, v5, vcc
	v_fmamk_f32 v10, v10, 0x3a000000, v94
	v_mul_f32_e32 v11, 0x4f800000, v10
	v_cmp_gt_f32_e32 vcc, s51, v10
	s_nop 1
	v_cndmask_b32_e32 v80, v10, v11, vcc
	v_sqrt_f32_e32 v82, v80
	global_load_dwordx4 v[14:17], v[8:9], off nt
	global_load_dwordx4 v[10:13], v[6:7], off offset:16 nt
	global_load_dwordx4 v[38:41], v[2:3], off offset:2048 nt
	global_load_dwordx4 v[34:37], v[2:3], off offset:3072 nt
	v_add_u32_e32 v2, -1, v82
	v_fma_f32 v3, -v2, v82, v80
	v_cmp_ge_f32_e64 s[4:5], 0, v3
	v_add_u32_e32 v3, 1, v82
	v_fma_f32 v6, -v3, v82, v80
	v_cndmask_b32_e64 v2, v82, v2, s[4:5]
	v_cmp_lt_f32_e64 s[4:5], 0, v6
	s_nop 1
	v_cndmask_b32_e64 v2, v2, v3, s[4:5]
	v_mul_f32_e32 v3, 0x37800000, v2
	v_cndmask_b32_e32 v2, v2, v3, vcc
	v_cmp_class_f32_e32 vcc, v80, v95
	s_nop 1
	v_cndmask_b32_e32 v80, v2, v80, vcc
	v_div_scale_f32 v82, s[4:5], v80, v80, 1.0
	v_rcp_f32_e32 v142, v82
	v_lshl_add_u64 v[2:3], v[4:5], 0, s[46:47]
	global_load_dwordx4 v[6:9], v[8:9], off offset:2048 nt
	s_nop 0
	global_load_dwordx4 v[2:5], v[2:3], off offset:16 nt
	v_fma_f32 v143, -v82, v142, 1.0
	v_fmac_f32_e32 v142, v143, v142
	v_div_scale_f32 v143, vcc, 1.0, v80, 1.0
	v_mul_f32_e32 v144, v143, v142
	v_fma_f32 v145, -v82, v144, v143
	v_fmac_f32_e32 v144, v145, v142
	v_fma_f32 v82, -v82, v144, v143
	v_div_fmas_f32 v82, v82, v142, v144
	v_div_fixup_f32 v142, v82, v80, 1.0
	v_mov_b32_e32 v144, v76
	v_mov_b32_e32 v145, v130
	v_pk_mul_f32 v[144:145], v[142:143], v[144:145] op_sel_hi:[0,1]
	v_mov_b32_e32 v130, v77
	v_pk_fma_f32 v[108:109], v[204:205], v[144:145], v[108:109]
	v_pk_mul_f32 v[76:77], v[142:143], v[130:131] op_sel_hi:[0,1]
	v_pk_fma_f32 v[104:105], v[200:201], v[76:77], v[104:105]
	v_bfe_u32 v76, v108, 16, 1
	v_pk_mul_f32 v[146:147], v[142:143], v[146:147] op_sel_hi:[0,1]
	v_add3_u32 v76, v108, v76, s3
	v_bfe_u32 v77, v109, 16, 1
	v_pk_fma_f32 v[110:111], v[206:207], v[146:147], v[110:111]
	v_lshrrev_b32_e32 v76, 16, v76
	v_add3_u32 v77, v109, v77, s3
	v_and_or_b32 v96, v77, s11, v76
	v_bfe_u32 v76, v110, 16, 1
	v_add3_u32 v76, v110, v76, s3
	v_bfe_u32 v77, v111, 16, 1
	v_lshrrev_b32_e32 v76, 16, v76
	v_add3_u32 v77, v111, v77, s3
	v_and_or_b32 v97, v77, s11, v76
	v_bfe_u32 v76, v104, 16, 1
	v_pk_mul_f32 v[100:101], v[142:143], v[134:135] op_sel_hi:[0,1]
	v_add3_u32 v76, v104, v76, s3
	v_bfe_u32 v77, v105, 16, 1
	v_pk_fma_f32 v[106:107], v[202:203], v[100:101], v[106:107]
	v_lshrrev_b32_e32 v76, 16, v76
	v_add3_u32 v77, v105, v77, s3
	v_and_or_b32 v98, v77, s11, v76
	v_bfe_u32 v76, v106, 16, 1
	v_add3_u32 v76, v106, v76, s3
	v_bfe_u32 v77, v107, 16, 1
	v_lshrrev_b32_e32 v76, 16, v76
	v_add3_u32 v77, v107, v77, s3
	v_and_or_b32 v99, v77, s11, v76
	v_lshl_add_u64 v[76:77], s[42:43], 0, v[66:67]
	global_store_dwordx4 v[76:77], v[96:99], off nt
	s_nop 0
	v_mov_b32_e32 v130, v136
	v_mov_b32_e32 v131, v138
	v_mov_b32_e32 v138, v137
	v_pk_mul_f32 v[130:131], v[142:143], v[130:131] op_sel_hi:[0,1]
	v_pk_mul_f32 v[132:133], v[142:143], v[138:139] op_sel_hi:[0,1]
	v_pk_mul_f32 v[128:129], v[142:143], v[128:129] op_sel_hi:[0,1]
	v_pk_mul_f32 v[134:135], v[142:143], v[140:141] op_sel_hi:[0,1]
	v_pk_mul_f32 v[78:79], v[142:143], v[78:79] op_sel_hi:[0,1]
	v_mul_f32_e32 v105, v105, v105
	v_mul_f32_e32 v107, v107, v107
	v_fmac_f32_e32 v105, v104, v104
	v_fmac_f32_e32 v107, v106, v106
	v_pk_mul_f32 v[72:73], v[142:143], v[72:73] op_sel_hi:[0,1]
	v_pk_mul_f32 v[74:75], v[142:143], v[74:75] op_sel_hi:[0,1]
	v_pk_mul_f32 v[70:71], v[142:143], v[70:71] op_sel_hi:[0,1]
	v_pk_mul_f32 v[68:69], v[142:143], v[68:69] op_sel_hi:[0,1]
	s_waitcnt vmcnt(0)
	v_pk_fma_f32 v[118:119], v[210:211], v[132:133], v[118:119]
	v_pk_fma_f32 v[116:117], v[208:209], v[130:131], v[116:117]
	v_pk_fma_f32 v[114:115], v[214:215], v[134:135], v[114:115]
	v_pk_fma_f32 v[112:113], v[212:213], v[128:129], v[112:113]
	v_bfe_u32 v80, v116, 16, 1
	v_bfe_u32 v96, v118, 16, 1
	v_bfe_u32 v98, v112, 16, 1
	v_bfe_u32 v100, v114, 16, 1
	v_bfe_u32 v82, v117, 16, 1
	v_bfe_u32 v97, v119, 16, 1
	v_bfe_u32 v99, v113, 16, 1
	v_bfe_u32 v101, v115, 16, 1
	v_add3_u32 v80, v116, v80, s3
	v_add3_u32 v96, v118, v96, s3
	v_add3_u32 v98, v112, v98, s3
	v_add3_u32 v100, v114, v100, s3
	v_add3_u32 v82, v117, v82, s3
	v_add3_u32 v97, v119, v97, s3
	v_add3_u32 v99, v113, v99, s3
	v_add3_u32 v101, v115, v101, s3
	v_lshrrev_b32_e32 v80, 16, v80
	v_lshrrev_b32_e32 v102, 16, v96
	v_lshrrev_b32_e32 v98, 16, v98
	v_lshrrev_b32_e32 v100, 16, v100
	v_and_or_b32 v96, v82, s11, v80
	v_and_or_b32 v97, v97, s11, v102
	v_and_or_b32 v98, v99, s11, v98
	v_and_or_b32 v99, v101, s11, v100
	global_store_dwordx4 v[76:77], v[96:99], off offset:1024 nt
	s_nop 0
	v_mov_b32_e32 v80, v83
	v_pk_mul_f32 v[80:81], v[142:143], v[80:81] op_sel_hi:[0,1]
	v_pk_mul_f32 v[82:83], v[142:143], v[84:85] op_sel_hi:[0,1]
	v_pk_mul_f32 v[84:85], v[142:143], v[86:87] op_sel_hi:[0,1]
	v_mul_f32_e32 v104, v119, v119
	v_mul_f32_e32 v106, v115, v115
	v_fmac_f32_e32 v104, v118, v118
	v_fmac_f32_e32 v106, v114, v114
	v_pk_fma_f32 v[86:87], v[218:219], v[78:79], v[122:123]
	v_pk_fma_f32 v[96:97], v[216:217], v[80:81], v[120:121]
	v_pk_fma_f32 v[98:99], v[222:223], v[84:85], v[126:127]
	v_pk_fma_f32 v[100:101], v[220:221], v[82:83], v[124:125]
	v_bfe_u32 v78, v96, 16, 1
	v_bfe_u32 v80, v86, 16, 1
	v_bfe_u32 v82, v100, 16, 1
	v_bfe_u32 v84, v98, 16, 1
	v_bfe_u32 v79, v97, 16, 1
	v_bfe_u32 v81, v87, 16, 1
	v_bfe_u32 v83, v101, 16, 1
	v_bfe_u32 v85, v99, 16, 1
	v_add3_u32 v78, v96, v78, s3
	v_add3_u32 v80, v86, v80, s3
	v_add3_u32 v82, v100, v82, s3
	v_add3_u32 v84, v98, v84, s3
	v_add3_u32 v79, v97, v79, s3
	v_add3_u32 v81, v87, v81, s3
; __device__ __forceinline__ unsigned pk2(float lo, float hi) { return f2bf(lo) | (f2bf(hi) << 16); }
; template <class Tv> __device__ __forceinline__ void ntstore(Tv v, Tv* p) { __builtin_nontemporal_store(v, p); }
; template <bool BASE_BF, bool OUT_BF>
; __device__ __forceinline__ void row_pass(const bf16* Y, const void* basev, int ldb, const float* gA, void* outv, int ldo, float* rs, const float* pin, int gw, int NGW, int lane) {
;     ...
;             for (int j = 0; j < 4; ++j) { const int c = j * 512 + lane * 8; const f32x4 g0 = *(const f32x4*)(gA + c), g1 = *(const f32x4*)(gA + c + 4);
;                 h[k][2 * j] = h[k][2 * j] + y[2 * j] * r1 * g0; h[k][2 * j + 1] = h[k][2 * j + 1] + y[2 * j + 1] * r1 * g1;
;                 if constexpr (OUT_BF) { const f32x4 a = h[k][2 * j], b = h[k][2 * j + 1]; v4u o; o.x = pk2(a.x, a.y); o.y = pk2(a.z, a.w); o.z = pk2(b.x, b.y); o.w = pk2(b.z, b.w); ntstore(o, (v4u*)(outb + row * ldo + c)); }
;                 else { ntstore(h[k][2 * j], (f32x4*)(outh + row * ldo + c)); ntstore(h[k][2 * j + 1], (f32x4*)(outh + row * ldo + c + 4)); } }
;             if (rs) {
; #pragma unroll
;                 for (int j = 0; j < 8; ++j) s2 += (h[k][j].x * h[k][j].x + h[k][j].y * h[k][j].y) + (h[k][j].z * h[k][j].z + h[k][j].w * h[k][j].w);
;                 const float r2 = 1.0f / sqrtf(wave_sum(s2) * (1.f / DM) + NORM_EPS);
;                 if (lane == 0) rs[row] = r2;
;             }
	v_add3_u32 v83, v101, v83, s3
	v_add3_u32 v85, v99, v85, s3
	v_lshrrev_b32_e32 v78, 16, v78
	v_lshrrev_b32_e32 v80, 16, v80
	v_lshrrev_b32_e32 v82, 16, v82
	v_lshrrev_b32_e32 v84, 16, v84
	v_and_or_b32 v78, v79, s11, v78
	v_and_or_b32 v79, v81, s11, v80
	v_and_or_b32 v80, v83, s11, v82
	v_and_or_b32 v81, v85, s11, v84
	global_store_dwordx4 v[76:77], v[78:81], off offset:2048 nt
	s_nop 0
	v_mul_f32_e32 v102, v109, v109
	v_mul_f32_e32 v103, v111, v111
	v_fmac_f32_e32 v102, v108, v108
	v_fmac_f32_e32 v103, v110, v110
	v_add_f32_e32 v102, v102, v103
	v_add_f32_e32 v103, v105, v107
	v_add_f32_e32 v102, v102, v103
	v_mul_f32_e32 v103, v117, v117
	v_mul_f32_e32 v105, v113, v113
	v_fmac_f32_e32 v103, v116, v116
	v_fmac_f32_e32 v105, v112, v112
	v_add_f32_e32 v103, v103, v104
	v_mul_f32_e32 v97, v97, v97
	v_mul_f32_e32 v87, v87, v87
	v_add_f32_e32 v104, v105, v106
	v_add_f32_e32 v102, v103, v102
	v_mul_f32_e32 v101, v101, v101
	v_mul_f32_e32 v99, v99, v99
	v_fmac_f32_e32 v97, v96, v96
	v_fmac_f32_e32 v87, v86, v86
	v_add_f32_e32 v102, v104, v102
	v_fmac_f32_e32 v101, v100, v100
	v_fmac_f32_e32 v99, v98, v98
	v_add_f32_e32 v86, v97, v87
	v_add_f32_e32 v87, v101, v99
	v_add_f32_e32 v86, v86, v102
	v_add_f32_e32 v86, v87, v86
	v_pk_fma_f32 v[56:57], v[74:75], v[226:227], v[56:57]
	v_pk_fma_f32 v[54:55], v[72:73], v[224:225], v[54:55]
	v_pk_fma_f32 v[68:69], v[68:69], v[230:231], v[52:53]
	v_pk_fma_f32 v[50:51], v[70:71], v[228:229], v[50:51]
	v_mul_f32_e32 v53, v55, v55
	v_mul_f32_e32 v70, v57, v57
	v_mul_f32_e32 v71, v51, v51
	v_mul_f32_e32 v72, v69, v69
	v_fmac_f32_e32 v53, v54, v54
	v_fmac_f32_e32 v70, v56, v56
	v_fmac_f32_e32 v71, v50, v50
	v_fmac_f32_e32 v72, v68, v68
	v_add_f32_e32 v53, v53, v70
	v_add_f32_e32 v53, v53, v86
	v_add_f32_e32 v70, v71, v72
	v_add_f32_e32 v53, v70, v53
	ds_bpermute_b32 v70, v88, v53
	v_bfe_u32 v52, v54, 16, 1
	v_add3_u32 v52, v54, v52, s3
	v_bfe_u32 v54, v55, 16, 1
	v_add3_u32 v54, v55, v54, s3
	s_waitcnt lgkmcnt(0)
	v_add_f32_e32 v53, v53, v70
	ds_bpermute_b32 v55, v89, v53
	v_lshrrev_b32_e32 v52, 16, v52
	v_and_or_b32 v52, v54, s11, v52
	v_bfe_u32 v54, v56, 16, 1
	v_add3_u32 v54, v56, v54, s3
	s_waitcnt lgkmcnt(0)
	v_add_f32_e32 v55, v53, v55
	ds_bpermute_b32 v56, v90, v55
	v_bfe_u32 v53, v57, 16, 1
	v_lshrrev_b32_e32 v54, 16, v54
	v_add3_u32 v53, v57, v53, s3
	v_and_or_b32 v53, v53, s11, v54
	s_waitcnt lgkmcnt(0)
	v_add_f32_e32 v55, v55, v56
	ds_bpermute_b32 v56, v91, v55
	v_bfe_u32 v54, v50, 16, 1
	v_add3_u32 v50, v50, v54, s3
	v_bfe_u32 v54, v51, 16, 1
	v_lshrrev_b32_e32 v50, 16, v50
	s_waitcnt lgkmcnt(0)
	v_add_f32_e32 v55, v55, v56
	ds_bpermute_b32 v56, v92, v55
	v_add3_u32 v51, v51, v54, s3
	v_and_or_b32 v54, v51, s11, v50
	v_bfe_u32 v50, v68, 16, 1
	v_add3_u32 v50, v68, v50, s3
	v_lshrrev_b32_e32 v57, 16, v50
	s_waitcnt lgkmcnt(0)
	v_add_f32_e32 v50, v55, v56
	ds_bpermute_b32 v51, v93, v50
	v_bfe_u32 v55, v69, 16, 1
	v_add3_u32 v55, v69, v55, s3
	v_and_or_b32 v55, v55, s11, v57
	global_store_dwordx4 v[76:77], v[52:55], off offset:3072 nt
	s_and_saveexec_b64 s[48:49], s[0:1]
	s_cbranch_execz .LBB0_1603
	s_waitcnt lgkmcnt(0)
	v_add_f32_e32 v50, v50, v51
	v_fmamk_f32 v50, v50, 0x3a000000, v94
	v_mul_f32_e32 v51, 0x4f800000, v50
	v_cmp_gt_f32_e32 vcc, s51, v50
	s_nop 1
	v_cndmask_b32_e32 v50, v50, v51, vcc
	v_sqrt_f32_e32 v51, v50
	s_nop 0
	v_add_u32_e32 v52, -1, v51
	v_fma_f32 v54, -v52, v51, v50
	v_add_u32_e32 v53, 1, v51
	v_cmp_ge_f32_e64 s[4:5], 0, v54
	s_nop 1
	v_cndmask_b32_e64 v52, v51, v52, s[4:5]
	v_fma_f32 v51, -v53, v51, v50
	v_cmp_lt_f32_e64 s[4:5], 0, v51
	s_nop 1
	v_cndmask_b32_e64 v51, v52, v53, s[4:5]
	v_mul_f32_e32 v52, 0x37800000, v51
	v_cndmask_b32_e32 v51, v51, v52, vcc
	v_cmp_class_f32_e32 vcc, v50, v95
	s_nop 1
	v_cndmask_b32_e32 v50, v51, v50, vcc
	v_div_scale_f32 v51, s[4:5], v50, v50, 1.0
	v_rcp_f32_e32 v52, v51
	s_add_u32 s4, s14, s40
	s_addc_u32 s5, s15, s41
	v_fma_f32 v53, -v51, v52, 1.0
	v_fmac_f32_e32 v52, v53, v52
	v_div_scale_f32 v53, vcc, 1.0, v50, 1.0
	v_mul_f32_e32 v54, v53, v52
	v_fma_f32 v55, -v51, v54, v53
	v_fmac_f32_e32 v54, v55, v52
	v_fma_f32 v51, -v51, v54, v53
	v_div_fmas_f32 v51, v51, v52, v54
	v_div_fixup_f32 v50, v51, v50, 1.0
	global_store_dword v59, v50, s[4:5]
.LBB0_1603:
	s_or_b64 exec, exec, s[48:49]
	v_lshlrev_b32_e32 v73, 16, v48
	v_and_b32_e32 v75, 0xffff0000, v48
	v_and_b32_e32 v74, 0xffff0000, v46
	v_lshlrev_b32_e32 v77, 16, v49
	v_and_b32_e32 v49, 0xffff0000, v49
	v_and_b32_e32 v48, 0xffff0000, v47
	v_lshlrev_b32_e32 v56, 16, v44
	v_and_b32_e32 v57, 0xffff0000, v44
	v_lshlrev_b32_e32 v55, 16, v38
	v_lshlrev_b32_e32 v72, 16, v46
	v_lshlrev_b32_e32 v76, 16, v47
	v_pk_mul_f32 v[46:47], v[74:75], v[74:75]
	v_pk_mul_f32 v[68:69], v[48:49], v[48:49]
	v_and_b32_e32 v81, 0xffff0000, v43
	v_and_b32_e32 v80, 0xffff0000, v42
	v_pk_fma_f32 v[46:47], v[72:73], v[72:73], v[46:47]
	v_pk_fma_f32 v[68:69], v[76:77], v[76:77], v[68:69]
	v_lshlrev_b32_e32 v79, 16, v43
	v_lshlrev_b32_e32 v78, 16, v42
	v_pk_mul_f32 v[42:43], v[80:81], v[80:81]
	v_mul_f32_e32 v54, v56, v56
	v_mul_f32_e32 v44, v57, v57
	v_lshlrev_b32_e32 v82, 16, v45
	v_and_b32_e32 v83, 0xffff0000, v45
	v_mov_b32_e32 v45, v55
	v_and_b32_e32 v53, 0xffff0000, v38
	v_lshlrev_b32_e32 v50, 16, v39
	s_waitcnt lgkmcnt(0)
; __device__ __forceinline__ unsigned pk2(float lo, float hi) { return f2bf(lo) | (f2bf(hi) << 16); }
; __device__ __forceinline__ float bflo(unsigned w) { return __uint_as_float(w << 16); }
; __device__ __forceinline__ float bfhi(unsigned w) { return __uint_as_float(w & 0xffff0000u); }
; template <class Tv> __device__ __forceinline__ void ntstore(Tv v, Tv* p) { __builtin_nontemporal_store(v, p); }
; template <bool BASE_BF, bool OUT_BF>
; __device__ __forceinline__ void row_pass(const bf16* Y, const void* basev, int ldb, const float* gA, void* outv, int ldo, float* rs, const float* pin, int gw, int NGW, int lane) {
;     ...
;         for (int k = 0; k < 2; ++k) { const size_t row = (size_t)(row0 + k * NGW);
;             f32x4 y[8]; float s = 0.f;
; #pragma unroll
;             for (int j = 0; j < 4; ++j) { const v4u w = yw[k][j]; y[2 * j] = (f32x4){bflo(w.x), bfhi(w.x), bflo(w.y), bfhi(w.y)}; y[2 * j + 1] = (f32x4){bflo(w.z), bfhi(w.z), bflo(w.w), bfhi(w.w)}; }
; #pragma unroll
;             for (int j = 0; j < 8; ++j) s += (y[j].x * y[j].x + y[j].y * y[j].y) + (y[j].z * y[j].z + y[j].w * y[j].w);
;             const float r1 = 1.0f / sqrtf(wave_sum(s) * (1.f / DM) + NORM_EPS); float s2 = 0.f;
; #pragma unroll
;             for (int j = 0; j < 4; ++j) { const int c = j * 512 + lane * 8; const f32x4 g0 = *(const f32x4*)(gA + c), g1 = *(const f32x4*)(gA + c + 4);
;                 h[k][2 * j] = h[k][2 * j] + y[2 * j] * r1 * g0; h[k][2 * j + 1] = h[k][2 * j + 1] + y[2 * j + 1] * r1 * g1;
;                 if constexpr (OUT_BF) { const f32x4 a = h[k][2 * j], b = h[k][2 * j + 1]; v4u o; o.x = pk2(a.x, a.y); o.y = pk2(a.z, a.w); o.z = pk2(b.x, b.y); o.w = pk2(b.z, b.w); ntstore(o, (v4u*)(outb + row * ldo + c)); }
;                 else { ntstore(h[k][2 * j], (f32x4*)(outh + row * ldo + c)); ntstore(h[k][2 * j + 1], (f32x4*)(outh + row * ldo + c + 4)); } }
	v_and_b32_e32 v51, 0xffff0000, v39
	v_pk_add_f32 v[46:47], v[46:47], v[68:69]
	v_pk_fma_f32 v[42:43], v[78:79], v[78:79], v[42:43]
	v_pk_add_f32 v[44:45], v[54:55], v[44:45]
	v_pk_mul_f32 v[68:69], v[54:55], v[54:55]
	v_mul_f32_e32 v52, v83, v83
	v_mul_f32_e32 v70, v53, v53
	v_mul_f32_e32 v71, v50, v50
	v_mul_f32_e32 v84, v51, v51
	v_mov_b32_e32 v45, v69
	v_pk_fma_f32 v[68:69], v[82:83], v[82:83], v[52:53] op_sel_hi:[1,1,0]
	v_pk_add_f32 v[46:47], v[46:47], v[46:47] op_sel:[0,1] op_sel_hi:[1,0]
	v_pk_add_f32 v[42:43], v[42:43], v[42:43] op_sel:[0,1] op_sel_hi:[1,0]
	v_mov_b32_e32 v69, v70
	v_mov_b32_e32 v47, v71
	v_mov_b32_e32 v43, v84
	v_pk_add_f32 v[44:45], v[44:45], v[68:69]
	v_pk_add_f32 v[42:43], v[46:47], v[42:43]
	v_lshlrev_b32_e32 v84, 16, v41
	v_pk_add_f32 v[42:43], v[44:45], v[42:43]
	v_and_b32_e32 v85, 0xffff0000, v41
	v_pk_add_f32 v[44:45], v[42:43], v[42:43] op_sel_hi:[0,1]
	v_lshlrev_b32_e32 v42, 16, v40
	v_and_b32_e32 v43, 0xffff0000, v40
	v_mul_f32_e32 v40, v42, v42
	v_pk_fma_f32 v[46:47], v[42:43], v[42:43], v[40:41] op_sel_hi:[1,1,0]
	v_mul_f32_e32 v40, v84, v84
	v_pk_fma_f32 v[68:69], v[84:85], v[84:85], v[40:41] op_sel_hi:[1,1,0]
	v_lshlrev_b32_e32 v40, 16, v34
	v_and_b32_e32 v41, 0xffff0000, v34
	v_mul_f32_e32 v34, v40, v40
	v_pk_fma_f32 v[70:71], v[40:41], v[40:41], v[34:35] op_sel_hi:[1,1,0]
	v_lshlrev_b32_e32 v34, 16, v35
	v_and_b32_e32 v35, 0xffff0000, v35
	v_mul_f32_e32 v44, v34, v34
	v_lshlrev_b32_e32 v38, 16, v36
	v_and_b32_e32 v39, 0xffff0000, v36
	v_lshlrev_b32_e32 v36, 16, v37
	v_and_b32_e32 v37, 0xffff0000, v37
	v_pk_fma_f32 v[86:87], v[34:35], v[34:35], v[44:45] op_sel_hi:[1,1,0]
	v_pk_add_f32 v[46:47], v[46:47], v[68:69]
	v_mul_f32_e32 v44, v39, v39
	v_mul_f32_e32 v70, v36, v36
	v_mul_f32_e32 v86, v37, v37
	v_mul_f32_e32 v96, v38, v38
	v_mov_b32_e32 v97, v47
	v_pk_add_f32 v[44:45], v[96:97], v[44:45]
	v_pk_add_f32 v[46:47], v[70:71], v[86:87]
	v_pk_add_f32 v[44:45], v[44:45], v[46:47]
	s_nop 0
	v_add_f32_e32 v52, v44, v45
	ds_bpermute_b32 v54, v88, v52
	s_waitcnt lgkmcnt(0)
	v_add_f32_e32 v52, v52, v54
	ds_bpermute_b32 v54, v89, v52
	s_waitcnt lgkmcnt(0)
	v_add_f32_e32 v52, v52, v54
	ds_bpermute_b32 v54, v90, v52
	s_waitcnt lgkmcnt(0)
	v_add_f32_e32 v52, v52, v54
	ds_bpermute_b32 v54, v91, v52
	s_waitcnt lgkmcnt(0)
	v_add_f32_e32 v52, v52, v54
	ds_bpermute_b32 v54, v92, v52
	s_waitcnt lgkmcnt(0)
	v_add_f32_e32 v52, v52, v54
	ds_bpermute_b32 v54, v93, v52
	s_waitcnt lgkmcnt(0)
	v_add_f32_e32 v52, v52, v54
	v_fmamk_f32 v52, v52, 0x3a000000, v94
	v_mul_f32_e32 v54, 0x4f800000, v52
	v_cmp_gt_f32_e32 vcc, s51, v52
	s_nop 1
	v_cndmask_b32_e32 v52, v52, v54, vcc
	v_sqrt_f32_e32 v54, v52
	s_nop 0
	v_add_u32_e32 v86, -1, v54
	v_fma_f32 v87, -v86, v54, v52
	v_cmp_ge_f32_e64 s[4:5], 0, v87
	v_add_u32_e32 v87, 1, v54
	s_nop 0
	v_cndmask_b32_e64 v86, v54, v86, s[4:5]
	v_fma_f32 v54, -v87, v54, v52
	v_cmp_lt_f32_e64 s[4:5], 0, v54
	s_nop 1
	v_cndmask_b32_e64 v54, v86, v87, s[4:5]
	v_mul_f32_e32 v86, 0x37800000, v54
	v_cndmask_b32_e32 v54, v54, v86, vcc
	v_cmp_class_f32_e32 vcc, v52, v95
	s_nop 1
	v_cndmask_b32_e32 v52, v54, v52, vcc
	v_div_scale_f32 v54, s[4:5], v52, v52, 1.0
	v_rcp_f32_e32 v86, v54
	s_nop 0
	v_fma_f32 v87, -v54, v86, 1.0
	v_fmac_f32_e32 v86, v87, v86
	v_div_scale_f32 v87, vcc, 1.0, v52, 1.0
	v_mul_f32_e32 v96, v87, v86
	v_fma_f32 v97, -v54, v96, v87
	v_fmac_f32_e32 v96, v97, v86
	v_fma_f32 v54, -v54, v96, v87
	v_div_fmas_f32 v54, v54, v86, v96
	v_div_fixup_f32 v54, v54, v52, 1.0
	v_mov_b32_e32 v86, v72
	v_mov_b32_e32 v87, v74
	v_pk_mul_f32 v[86:87], v[54:55], v[86:87] op_sel_hi:[0,1]
	v_mov_b32_e32 v74, v73
	v_pk_fma_f32 v[86:87], v[204:205], v[86:87], v[30:31]
	v_pk_mul_f32 v[30:31], v[54:55], v[74:75] op_sel_hi:[0,1]
	v_mov_b32_e32 v96, v76
	v_mov_b32_e32 v97, v48
	v_pk_fma_f32 v[68:69], v[200:201], v[30:31], v[26:27]
	v_bfe_u32 v26, v86, 16, 1
	v_pk_mul_f32 v[96:97], v[54:55], v[96:97] op_sel_hi:[0,1]
	v_mov_b32_e32 v48, v77
	v_add3_u32 v26, v86, v26, s3
	v_bfe_u32 v27, v87, 16, 1
	v_pk_fma_f32 v[32:33], v[206:207], v[96:97], v[32:33]
	v_pk_mul_f32 v[44:45], v[54:55], v[48:49] op_sel_hi:[0,1]
	v_lshrrev_b32_e32 v26, 16, v26
	v_add3_u32 v27, v87, v27, s3
	v_pk_fma_f32 v[48:49], v[202:203], v[44:45], v[28:29]
	v_and_or_b32 v28, v27, s11, v26
	v_bfe_u32 v26, v32, 16, 1
	v_add3_u32 v26, v32, v26, s3
	v_bfe_u32 v27, v33, 16, 1
	v_lshrrev_b32_e32 v26, 16, v26
	v_add3_u32 v27, v33, v27, s3
	v_and_or_b32 v29, v27, s11, v26
	v_bfe_u32 v26, v68, 16, 1
	v_add3_u32 v26, v68, v26, s3
	v_bfe_u32 v27, v69, 16, 1
	v_lshrrev_b32_e32 v26, 16, v26
	v_add3_u32 v27, v69, v27, s3
	v_and_or_b32 v30, v27, s11, v26
	v_bfe_u32 v26, v48, 16, 1
	v_add3_u32 v26, v48, v26, s3
	v_bfe_u32 v27, v49, 16, 1
	v_lshrrev_b32_e32 v26, 16, v26
	v_add3_u32 v27, v49, v27, s3
	v_and_or_b32 v31, v27, s11, v26
	v_lshl_add_u64 v[26:27], s[36:37], 0, v[66:67]
	global_store_dwordx4 v[26:27], v[28:31], off nt
	s_nop 0
	v_mov_b32_e32 v70, v78
	v_mov_b32_e32 v71, v80
	v_pk_mul_f32 v[70:71], v[54:55], v[70:71] op_sel_hi:[0,1]
	v_mov_b32_e32 v80, v79
	v_pk_mul_f32 v[72:73], v[54:55], v[80:81] op_sel_hi:[0,1]
	v_mov_b32_e32 v52, v55
	v_pk_mul_f32 v[52:53], v[54:55], v[52:53] op_sel_hi:[0,1]
	v_pk_mul_f32 v[50:51], v[54:55], v[50:51] op_sel_hi:[0,1]
	v_pk_mul_f32 v[42:43], v[54:55], v[42:43] op_sel_hi:[0,1]
	v_mul_f32_e32 v33, v33, v33
	v_mul_f32_e32 v49, v49, v49
	v_fmac_f32_e32 v33, v32, v32
	v_fmac_f32_e32 v49, v48, v48
	v_pk_mul_f32 v[40:41], v[54:55], v[40:41] op_sel_hi:[0,1]
	v_pk_mul_f32 v[34:35], v[54:55], v[34:35] op_sel_hi:[0,1]
	v_pk_mul_f32 v[38:39], v[54:55], v[38:39] op_sel_hi:[0,1]
	v_pk_mul_f32 v[36:37], v[54:55], v[36:37] op_sel_hi:[0,1]
; __device__ __forceinline__ unsigned pk2(float lo, float hi) { return f2bf(lo) | (f2bf(hi) << 16); }
; template <class Tv> __device__ __forceinline__ void ntstore(Tv v, Tv* p) { __builtin_nontemporal_store(v, p); }
; template <bool BASE_BF, bool OUT_BF>
; __device__ __forceinline__ void row_pass(const bf16* Y, const void* basev, int ldb, const float* gA, void* outv, int ldo, float* rs, const float* pin, int gw, int NGW, int lane) {
;     ...
;             for (int j = 0; j < 4; ++j) { const int c = j * 512 + lane * 8; const f32x4 g0 = *(const f32x4*)(gA + c), g1 = *(const f32x4*)(gA + c + 4);
;                 h[k][2 * j] = h[k][2 * j] + y[2 * j] * r1 * g0; h[k][2 * j + 1] = h[k][2 * j + 1] + y[2 * j + 1] * r1 * g1;
;                 if constexpr (OUT_BF) { const f32x4 a = h[k][2 * j], b = h[k][2 * j + 1]; v4u o; o.x = pk2(a.x, a.y); o.y = pk2(a.z, a.w); o.z = pk2(b.x, b.y); o.w = pk2(b.z, b.w); ntstore(o, (v4u*)(outb + row * ldo + c)); }
;                 else { ntstore(h[k][2 * j], (f32x4*)(outh + row * ldo + c)); ntstore(h[k][2 * j + 1], (f32x4*)(outh + row * ldo + c + 4)); } }
;             if (rs) {
; #pragma unroll
;                 for (int j = 0; j < 8; ++j) s2 += (h[k][j].x * h[k][j].x + h[k][j].y * h[k][j].y) + (h[k][j].z * h[k][j].z + h[k][j].w * h[k][j].w);
;                 const float r2 = 1.0f / sqrtf(wave_sum(s2) * (1.f / DM) + NORM_EPS);
;                 if (lane == 0) rs[row] = r2;
;             }
	v_pk_fma_f32 v[28:29], v[208:209], v[70:71], v[22:23]
	v_pk_mul_f32 v[22:23], v[54:55], v[56:57] op_sel_hi:[0,1]
	v_pk_fma_f32 v[44:45], v[212:213], v[22:23], v[18:19]
	v_bfe_u32 v18, v28, 16, 1
	v_add3_u32 v18, v28, v18, s3
	v_bfe_u32 v19, v29, 16, 1
	v_pk_fma_f32 v[30:31], v[210:211], v[72:73], v[24:25]
	v_lshrrev_b32_e32 v18, 16, v18
	v_add3_u32 v19, v29, v19, s3
	v_pk_mul_f32 v[24:25], v[54:55], v[82:83] op_sel_hi:[0,1]
	v_and_or_b32 v18, v19, s11, v18
	v_bfe_u32 v19, v30, 16, 1
	v_pk_fma_f32 v[46:47], v[214:215], v[24:25], v[20:21]
	v_add3_u32 v19, v30, v19, s3
	v_bfe_u32 v20, v31, 16, 1
	v_lshrrev_b32_e32 v19, 16, v19
	v_add3_u32 v20, v31, v20, s3
	v_and_or_b32 v19, v20, s11, v19
	v_bfe_u32 v20, v44, 16, 1
	v_add3_u32 v20, v44, v20, s3
	v_bfe_u32 v21, v45, 16, 1
	v_lshrrev_b32_e32 v20, 16, v20
	v_add3_u32 v21, v45, v21, s3
	v_and_or_b32 v20, v21, s11, v20
	v_bfe_u32 v21, v46, 16, 1
	v_add3_u32 v21, v46, v21, s3
	v_bfe_u32 v22, v47, 16, 1
	v_lshrrev_b32_e32 v21, 16, v21
	v_add3_u32 v22, v47, v22, s3
	v_and_or_b32 v21, v22, s11, v21
	global_store_dwordx4 v[26:27], v[18:21], off offset:1024 nt
	s_nop 0
	v_pk_mul_f32 v[56:57], v[54:55], v[84:85] op_sel_hi:[0,1]
	v_mul_f32_e32 v29, v29, v29
	v_mul_f32_e32 v31, v31, v31
	v_fmac_f32_e32 v29, v28, v28
	v_fmac_f32_e32 v31, v30, v30
	v_add_f32_e32 v28, v29, v31
	v_pk_fma_f32 v[20:21], v[218:219], v[50:51], v[16:17]
	v_pk_fma_f32 v[18:19], v[216:217], v[52:53], v[14:15]
	v_pk_fma_f32 v[24:25], v[222:223], v[56:57], v[12:13]
	v_pk_fma_f32 v[22:23], v[220:221], v[42:43], v[10:11]
	v_bfe_u32 v10, v18, 16, 1
	v_bfe_u32 v12, v20, 16, 1
	v_bfe_u32 v14, v22, 16, 1
	v_bfe_u32 v16, v24, 16, 1
	v_bfe_u32 v11, v19, 16, 1
	v_bfe_u32 v13, v21, 16, 1
	v_bfe_u32 v15, v23, 16, 1
	v_bfe_u32 v17, v25, 16, 1
	v_add3_u32 v10, v18, v10, s3
	v_add3_u32 v12, v20, v12, s3
	v_add3_u32 v14, v22, v14, s3
	v_add3_u32 v16, v24, v16, s3
	v_add3_u32 v11, v19, v11, s3
	v_add3_u32 v13, v21, v13, s3
	v_add3_u32 v15, v23, v15, s3
	v_add3_u32 v17, v25, v17, s3
	v_lshrrev_b32_e32 v10, 16, v10
	v_lshrrev_b32_e32 v12, 16, v12
	v_lshrrev_b32_e32 v14, 16, v14
	v_lshrrev_b32_e32 v16, 16, v16
	v_and_or_b32 v10, v11, s11, v10
	v_and_or_b32 v11, v13, s11, v12
	v_and_or_b32 v12, v15, s11, v14
	v_and_or_b32 v13, v17, s11, v16
	global_store_dwordx4 v[26:27], v[10:13], off offset:2048 nt
	s_nop 0
	v_mul_f32_e32 v42, v87, v87
	v_mul_f32_e32 v43, v69, v69
	v_fmac_f32_e32 v42, v86, v86
	v_fmac_f32_e32 v43, v68, v68
	v_add_f32_e32 v32, v42, v33
	v_add_f32_e32 v33, v43, v49
	v_add_f32_e32 v32, v32, v33
	v_mul_f32_e32 v33, v45, v45
	v_mul_f32_e32 v42, v47, v47
	v_fmac_f32_e32 v33, v44, v44
	v_fmac_f32_e32 v42, v46, v46
	v_mul_f32_e32 v19, v19, v19
	v_mul_f32_e32 v21, v21, v21
	v_add_f32_e32 v29, v33, v42
	v_add_f32_e32 v28, v28, v32
	v_mul_f32_e32 v23, v23, v23
	v_mul_f32_e32 v25, v25, v25
	v_fmac_f32_e32 v19, v18, v18
	v_fmac_f32_e32 v21, v20, v20
	v_add_f32_e32 v28, v29, v28
	v_fmac_f32_e32 v23, v22, v22
	v_fmac_f32_e32 v25, v24, v24
	v_add_f32_e32 v18, v19, v21
	v_add_f32_e32 v19, v23, v25
	v_add_f32_e32 v18, v18, v28
	v_add_f32_e32 v18, v19, v18
	v_pk_fma_f32 v[8:9], v[34:35], v[226:227], v[8:9]
	v_pk_fma_f32 v[6:7], v[40:41], v[224:225], v[6:7]
	v_pk_fma_f32 v[10:11], v[36:37], v[230:231], v[4:5]
	v_pk_fma_f32 v[2:3], v[38:39], v[228:229], v[2:3]
	v_mul_f32_e32 v5, v7, v7
	v_mul_f32_e32 v12, v9, v9
	v_mul_f32_e32 v13, v3, v3
	v_mul_f32_e32 v14, v11, v11
	v_fmac_f32_e32 v5, v6, v6
	v_fmac_f32_e32 v12, v8, v8
	v_fmac_f32_e32 v13, v2, v2
	v_fmac_f32_e32 v14, v10, v10
	v_add_f32_e32 v5, v5, v12
	v_add_f32_e32 v5, v5, v18
	v_add_f32_e32 v12, v13, v14
	v_add_f32_e32 v5, v12, v5
	ds_bpermute_b32 v12, v88, v5
	v_bfe_u32 v4, v6, 16, 1
	v_add3_u32 v4, v6, v4, s3
	v_bfe_u32 v6, v7, 16, 1
	v_add3_u32 v6, v7, v6, s3
	s_waitcnt lgkmcnt(0)
	v_add_f32_e32 v5, v5, v12
	ds_bpermute_b32 v7, v89, v5
	v_lshrrev_b32_e32 v4, 16, v4
	v_and_or_b32 v4, v6, s11, v4
	v_bfe_u32 v6, v8, 16, 1
	v_add3_u32 v6, v8, v6, s3
	s_waitcnt lgkmcnt(0)
	v_add_f32_e32 v7, v5, v7
	ds_bpermute_b32 v8, v90, v7
	v_bfe_u32 v5, v9, 16, 1
	v_lshrrev_b32_e32 v6, 16, v6
	v_add3_u32 v5, v9, v5, s3
	v_and_or_b32 v5, v5, s11, v6
	s_waitcnt lgkmcnt(0)
	v_add_f32_e32 v7, v7, v8
	ds_bpermute_b32 v8, v91, v7
	v_bfe_u32 v6, v2, 16, 1
	v_add3_u32 v2, v2, v6, s3
	v_bfe_u32 v6, v3, 16, 1
	v_lshrrev_b32_e32 v2, 16, v2
	s_waitcnt lgkmcnt(0)
	v_add_f32_e32 v7, v7, v8
	ds_bpermute_b32 v8, v92, v7
	v_add3_u32 v3, v3, v6, s3
	v_and_or_b32 v6, v3, s11, v2
	v_bfe_u32 v2, v10, 16, 1
	v_add3_u32 v2, v10, v2, s3
	v_lshrrev_b32_e32 v9, 16, v2
	s_waitcnt lgkmcnt(0)
	v_add_f32_e32 v2, v7, v8
	ds_bpermute_b32 v3, v93, v2
	v_bfe_u32 v7, v11, 16, 1
	v_add3_u32 v7, v11, v7, s3
	v_and_or_b32 v7, v7, s11, v9
	global_store_dwordx4 v[26:27], v[4:7], off offset:3072 nt
	s_and_saveexec_b64 s[48:49], s[0:1]
	s_cbranch_execz .LBB0_1600
	s_waitcnt lgkmcnt(0)
	v_add_f32_e32 v2, v2, v3
	v_fmamk_f32 v2, v2, 0x3a000000, v94
	v_mul_f32_e32 v3, 0x4f800000, v2
	v_cmp_gt_f32_e32 vcc, s51, v2
	s_nop 1
	v_cndmask_b32_e32 v2, v2, v3, vcc
	v_sqrt_f32_e32 v3, v2
	s_nop 0
	v_add_u32_e32 v4, -1, v3
	v_fma_f32 v6, -v4, v3, v2
	v_add_u32_e32 v5, 1, v3
	v_cmp_ge_f32_e64 s[4:5], 0, v6
	s_nop 1
	v_cndmask_b32_e64 v4, v3, v4, s[4:5]
	v_fma_f32 v3, -v5, v3, v2
	v_cmp_lt_f32_e64 s[4:5], 0, v3
	s_nop 1
	v_cndmask_b32_e64 v3, v4, v5, s[4:5]
	v_mul_f32_e32 v4, 0x37800000, v3
	v_cndmask_b32_e32 v3, v3, v4, vcc
	v_cmp_class_f32_e32 vcc, v2, v95
	s_nop 1
	v_cndmask_b32_e32 v2, v3, v2, vcc
	v_div_scale_f32 v3, s[4:5], v2, v2, 1.0
	v_rcp_f32_e32 v4, v3
	s_add_u32 s4, s14, s16
	s_addc_u32 s5, s15, s17
	v_fma_f32 v5, -v3, v4, 1.0
	v_fmac_f32_e32 v4, v5, v4
	v_div_scale_f32 v5, vcc, 1.0, v2, 1.0
	v_mul_f32_e32 v6, v5, v4
	v_fma_f32 v7, -v3, v6, v5
	v_fmac_f32_e32 v6, v7, v4
	v_fma_f32 v3, -v3, v6, v5
	v_div_fmas_f32 v3, v3, v4, v6
	v_div_fixup_f32 v2, v3, v2, 1.0
	global_store_dword v59, v2, s[4:5]
	s_branch .LBB0_1600
